# GEMM accumulator zeroing at each unit start done with 64-bit moves (half the instructions)
# baseline (speedup 1.0000x reference)
; template <int AM, bool FP8, class PH>
; __device__ __forceinline__ void gemm_stream(PH& ph, const int nu, const int lda, const int ldb, const int K) {
;     ...
;   for (int u = 0; u < nu; ++u) {
; #pragma unroll
;     for (int a = 0; a < 2; ++a)
; #pragma unroll
;       for (int b = 0; b < 2; ++b)
; #pragma unroll
;         for (int m = 0; m < AM; ++m)
; #pragma unroll
;           for (int n = 0; n < 2; ++n) acc[a][b][m][n] = f32x4{0.f, 0.f, 0.f, 0.f};
.LBB0_95:
	s_lshr_b32 s4, s89, 2
	v_readlane_b32 s54, v254, 3
	s_mul_i32 s4, s4, s54
	v_readlane_b32 s5, v254, 0
	v_readlane_b32 s55, v254, 4
	s_add_i32 s4, s4, s5
	s_ashr_i32 s5, s4, 2
	s_lshl_b32 s55, s89, 10
	s_lshl_b32 s4, s4, 8
	s_mul_hi_i32 s54, s5, 0x250000
	s_mul_i32 s5, s5, 0x250000
	s_and_b32 s55, s55, 0xc00
	s_and_b32 s88, s4, 0x300
	s_add_u32 s56, s44, s5
	s_addc_u32 s57, s45, s54
	s_add_u32 s4, s56, s55
	s_addc_u32 s5, s57, 0
	s_add_u32 s4, s4, s88
	s_addc_u32 s5, s5, 0
	s_add_u32 s58, s4, 0x2a00
	s_addc_u32 s59, s5, 0
	s_add_u32 s66, s50, 0x100
	v_mov_b32_e32 v2, 0
	s_addc_u32 s67, s51, 0
	s_mov_b64 s[68:69], 0
	s_mov_b32 s4, -2
	v_mov_b32_e32 v3, 0
	v_mov_b64_e32 v[4:5], 0
	v_mov_b64_e32 v[6:7], 0
	v_mov_b64_e32 v[8:9], 0
	v_mov_b64_e32 v[18:19], 0
	v_mov_b64_e32 v[20:21], 0
	v_mov_b64_e32 v[22:23], 0
	v_mov_b64_e32 v[24:25], 0
	v_mov_b64_e32 v[10:11], 0
	v_mov_b64_e32 v[12:13], 0
	v_mov_b64_e32 v[14:15], 0
	v_mov_b64_e32 v[16:17], 0
	v_mov_b64_e32 v[26:27], 0
	v_mov_b64_e32 v[28:29], 0
	v_mov_b64_e32 v[30:31], 0
	v_mov_b64_e32 v[32:33], 0
	v_mov_b64_e32 v[34:35], 0
	v_mov_b64_e32 v[36:37], 0
	v_mov_b64_e32 v[38:39], 0
	v_mov_b64_e32 v[40:41], 0
	v_mov_b64_e32 v[50:51], 0
	v_mov_b64_e32 v[52:53], 0
	v_mov_b64_e32 v[54:55], 0
	v_mov_b64_e32 v[56:57], 0
	v_mov_b64_e32 v[42:43], 0
	v_mov_b64_e32 v[44:45], 0
	v_mov_b64_e32 v[46:47], 0
	v_mov_b64_e32 v[48:49], 0
	v_mov_b64_e32 v[58:59], 0
	v_mov_b64_e32 v[60:61], 0
	v_mov_b64_e32 v[62:63], 0
	v_mov_b64_e32 v[64:65], 0
	s_branch .LBB0_97

; #define BAR __builtin_amdgcn_s_barrier()
; template <int AM, bool FP8, class PH>
; __device__ __forceinline__ void gemm_stream(PH& ph, const int nu, const int lda, const int ldb, const int K) {
;     ...
;   for (int u = 0; u < nu; ++u) {
; #pragma unroll
;     for (int a = 0; a < 2; ++a)
; #pragma unroll
;       for (int b = 0; b < 2; ++b)
; #pragma unroll
;         for (int m = 0; m < AM; ++m)
; #pragma unroll
;           for (int n = 0; n < 2; ++n) acc[a][b][m][n] = f32x4{0.f, 0.f, 0.f, 0.f};
;     if (u > 0) { if (wr == 1) BAR; }
;     const bool has_next = (u + 1 < nu);
;     GUnit nx = cur;
;     if (has_next) nx = ph.unit(u + 1);
.LBB0_222:
	s_add_u32 s4, s58, 0x100
	s_waitcnt lgkmcnt(0)
	v_mov_b32_e32 v2, 0
	s_addc_u32 s5, s59, 0
	s_mov_b32 s66, -2
	v_mov_b32_e32 v3, 0
	v_mov_b64_e32 v[4:5], 0
	v_mov_b64_e32 v[6:7], 0
	v_mov_b64_e32 v[8:9], 0
	v_mov_b64_e32 v[18:19], 0
	v_mov_b64_e32 v[20:21], 0
	v_mov_b64_e32 v[22:23], 0
	v_mov_b64_e32 v[24:25], 0
	v_mov_b64_e32 v[34:35], 0
	v_mov_b64_e32 v[36:37], 0
	v_mov_b64_e32 v[38:39], 0
	v_mov_b64_e32 v[40:41], 0
	v_mov_b64_e32 v[54:55], 0
	v_mov_b64_e32 v[56:57], 0
	v_mov_b64_e32 v[58:59], 0
	v_mov_b64_e32 v[60:61], 0
	v_mov_b64_e32 v[10:11], 0
	v_mov_b64_e32 v[12:13], 0
	v_mov_b64_e32 v[14:15], 0
	v_mov_b64_e32 v[16:17], 0
	v_mov_b64_e32 v[26:27], 0
	v_mov_b64_e32 v[28:29], 0
	v_mov_b64_e32 v[30:31], 0
	v_mov_b64_e32 v[32:33], 0
	v_mov_b64_e32 v[42:43], 0
	v_mov_b64_e32 v[44:45], 0
	v_mov_b64_e32 v[46:47], 0
	v_mov_b64_e32 v[48:49], 0
	v_mov_b64_e32 v[62:63], 0
	v_mov_b64_e32 v[64:65], 0
	v_mov_b64_e32 v[66:67], 0
	v_mov_b64_e32 v[68:69], 0
	v_mov_b64_e32 v[70:71], 0
	v_mov_b64_e32 v[72:73], 0
	v_mov_b64_e32 v[74:75], 0
	v_mov_b64_e32 v[76:77], 0
	v_mov_b64_e32 v[86:87], 0
	v_mov_b64_e32 v[88:89], 0
	v_mov_b64_e32 v[90:91], 0
	v_mov_b64_e32 v[92:93], 0
	v_mov_b64_e32 v[102:103], 0
	v_mov_b64_e32 v[104:105], 0
	v_mov_b64_e32 v[106:107], 0
	v_mov_b64_e32 v[108:109], 0
	v_mov_b64_e32 v[118:119], 0
	v_mov_b64_e32 v[120:121], 0
	v_mov_b64_e32 v[122:123], 0
	v_mov_b64_e32 v[124:125], 0
	v_mov_b64_e32 v[78:79], 0
	v_mov_b64_e32 v[80:81], 0
	v_mov_b64_e32 v[82:83], 0
	v_mov_b64_e32 v[84:85], 0
	v_mov_b64_e32 v[94:95], 0
	v_mov_b64_e32 v[96:97], 0
	v_mov_b64_e32 v[98:99], 0
	v_mov_b64_e32 v[100:101], 0
	v_mov_b64_e32 v[110:111], 0
	v_mov_b64_e32 v[112:113], 0
	v_mov_b64_e32 v[114:115], 0
	v_mov_b64_e32 v[116:117], 0
	v_mov_b64_e32 v[126:127], 0
	v_mov_b64_e32 v[128:129], 0
	v_mov_b64_e32 v[50:51], 0
	v_mov_b64_e32 v[52:53], 0
	s_mov_b64 s[80:81], 0x128000
	s_mov_b64 s[82:83], 0x128080

; #define BAR __builtin_amdgcn_s_barrier()
; template <int AM, bool FP8, class PH>
; __device__ __forceinline__ void gemm_stream(PH& ph, const int nu, const int lda, const int ldb, const int K) {
;     ...
;   for (int u = 0; u < nu; ++u) {
; #pragma unroll
;     for (int a = 0; a < 2; ++a)
; #pragma unroll
;       for (int b = 0; b < 2; ++b)
; #pragma unroll
;         for (int m = 0; m < AM; ++m)
; #pragma unroll
;           for (int n = 0; n < 2; ++n) acc[a][b][m][n] = f32x4{0.f, 0.f, 0.f, 0.f};
;     if (u > 0) { if (wr == 1) BAR; }
;     const bool has_next = (u + 1 < nu);
;     GUnit nx = cur;
;     if (has_next) nx = ph.unit(u + 1);
.LBB0_346:
	s_add_u32 s4, s46, 0x100
	v_mov_b32_e32 v2, 0
	s_addc_u32 s5, s47, 0
	s_mov_b32 s74, -2
	v_mov_b32_e32 v3, 0
	v_mov_b64_e32 v[4:5], 0
	v_mov_b64_e32 v[6:7], 0
	v_mov_b64_e32 v[8:9], 0
	v_mov_b64_e32 v[18:19], 0
	v_mov_b64_e32 v[20:21], 0
	v_mov_b64_e32 v[22:23], 0
	v_mov_b64_e32 v[24:25], 0
	v_mov_b64_e32 v[34:35], 0
	v_mov_b64_e32 v[36:37], 0
	v_mov_b64_e32 v[38:39], 0
	v_mov_b64_e32 v[40:41], 0
	v_mov_b64_e32 v[50:51], 0
	v_mov_b64_e32 v[52:53], 0
	v_mov_b64_e32 v[54:55], 0
	v_mov_b64_e32 v[56:57], 0
	v_mov_b64_e32 v[10:11], 0
	v_mov_b64_e32 v[12:13], 0
	v_mov_b64_e32 v[14:15], 0
	v_mov_b64_e32 v[16:17], 0
	v_mov_b64_e32 v[26:27], 0
	v_mov_b64_e32 v[28:29], 0
	v_mov_b64_e32 v[30:31], 0
	v_mov_b64_e32 v[32:33], 0
	v_mov_b64_e32 v[42:43], 0
	v_mov_b64_e32 v[44:45], 0
	v_mov_b64_e32 v[46:47], 0
	v_mov_b64_e32 v[48:49], 0
	v_mov_b64_e32 v[58:59], 0
	v_mov_b64_e32 v[60:61], 0
	v_mov_b64_e32 v[62:63], 0
	v_mov_b64_e32 v[64:65], 0
	v_mov_b64_e32 v[66:67], 0
	v_mov_b64_e32 v[68:69], 0
	v_mov_b64_e32 v[70:71], 0
	v_mov_b64_e32 v[72:73], 0
	v_mov_b64_e32 v[82:83], 0
	v_mov_b64_e32 v[84:85], 0
	v_mov_b64_e32 v[86:87], 0
	v_mov_b64_e32 v[88:89], 0
	v_mov_b64_e32 v[98:99], 0
	v_mov_b64_e32 v[100:101], 0
	v_mov_b64_e32 v[102:103], 0
	v_mov_b64_e32 v[104:105], 0
	v_mov_b64_e32 v[114:115], 0
	v_mov_b64_e32 v[116:117], 0
	v_mov_b64_e32 v[118:119], 0
	v_mov_b64_e32 v[120:121], 0
	v_mov_b64_e32 v[74:75], 0
	v_mov_b64_e32 v[76:77], 0
	v_mov_b64_e32 v[78:79], 0
	v_mov_b64_e32 v[80:81], 0
	v_mov_b64_e32 v[90:91], 0
	v_mov_b64_e32 v[92:93], 0
	v_mov_b64_e32 v[94:95], 0
	v_mov_b64_e32 v[96:97], 0
	v_mov_b64_e32 v[106:107], 0
	v_mov_b64_e32 v[108:109], 0
	v_mov_b64_e32 v[110:111], 0
	v_mov_b64_e32 v[112:113], 0
	v_mov_b64_e32 v[122:123], 0
	v_mov_b64_e32 v[124:125], 0
	v_mov_b64_e32 v[126:127], 0
	v_mov_b64_e32 v[128:129], 0
	s_mov_b64 s[54:55], 0x30080

;   __device__ __forceinline__ void locate(int u, const bf16_t*& A, const bf16_t*& Bt, const float*& ssq, bf16_t*& out, int& ldo) const {
;     const int i = blockIdx.x + u * gridDim.x;
;     if (i < NT1) {
;       int pm, pn; tile_remap(i, nM, nN, pm, pn);
;       pn = nN - 1 - pn;
;       A = p->xb + ((long)c * CT + pm * 256) * DM; Bt = p->WinT + ((long)l * INW + pn * 256) * DM;
;       ssq = p->ssq_x + (long)l * NTOK + c * CT + pm * 256; out = p->proj + (long)pm * 256 * INW + pn * 256; ldo = INW;
.LBB0_367:
	v_readlane_b32 s4, v254, 3
	s_mul_i32 s13, s13, s4
	v_readlane_b32 s4, v254, 0
	s_add_i32 s13, s13, s4
	s_cmpk_lt_i32 s13, 0x540
	v_readlane_b32 s5, v254, 4
	s_cselect_b64 s[56:57], -1, 0
	s_cmpk_gt_i32 s13, 0x53f
	s_cselect_b64 s[46:47], -1, 0
	s_ashr_i32 s5, s13, 31
	s_lshr_b32 s5, s5, 29
	s_add_i32 s5, s13, s5
	s_ashr_i32 s30, s5, 3
	s_and_b32 s5, s5, -8
	s_sub_i32 s5, s13, s5
	s_lshr_b32 s31, s5, 31
	s_or_b32 s31, s31, 0xa8
	s_mul_i32 s5, s31, s5
	s_add_i32 s5, s5, s30
	s_mul_hi_i32 s30, s5, 0x30c30c31
	s_lshr_b32 s31, s30, 31
	s_ashr_i32 s30, s30, 5
	s_add_i32 s30, s30, s31
	s_lshl_b32 s31, s30, 3
	s_sub_i32 s52, 64, s31
	s_min_u32 s52, s52, 8
	s_mulk_i32 s30, 0xa8
	s_sub_i32 s30, s5, s30
	v_cvt_f32_ubyte0_e32 v2, s52
	v_cvt_f32_i32_e32 v0, s30
	v_rcp_iflag_f32_e32 v3, v2
	s_lshl_b32 s4, s13, 6
	s_and_b32 s54, s4, 0x300
	s_ashr_i32 s4, s30, 30
	v_mul_f32_e32 v3, v0, v3
	v_trunc_f32_e32 v3, v3
	v_fma_f32 v0, -v3, v2, v0
	v_cvt_i32_f32_e32 v3, v3
	s_or_b32 s53, s4, 1
	v_cmp_ge_f32_e64 s[4:5], |v0|, v2
	s_and_b64 s[4:5], s[4:5], exec
	s_cselect_b32 s4, s53, 0
	v_readfirstlane_b32 s78, v3
	s_add_i32 s78, s78, s4
	s_mul_i32 s4, s78, s52
	s_sub_i32 s4, s30, s4
	s_sext_i32_i16 s4, s4
	s_add_i32 s31, s31, s4
	s_lshl_b32 s4, s31, 8
	s_ashr_i32 s5, s4, 31
	s_add_u32 s52, s42, 0x100
	v_mov_b32_e32 v2, 0
	s_addc_u32 s53, s43, 0
	s_mov_b64 s[58:59], 0
	s_mov_b32 s30, -2
	s_lshl_b32 s92, s54, 2
	s_lshl_b64 s[66:67], s[4:5], 2
	v_mov_b32_e32 v3, 0
	v_mov_b64_e32 v[4:5], 0
	v_mov_b64_e32 v[6:7], 0
	v_mov_b64_e32 v[8:9], 0
	v_mov_b64_e32 v[18:19], 0
	v_mov_b64_e32 v[20:21], 0
	v_mov_b64_e32 v[22:23], 0
	v_mov_b64_e32 v[24:25], 0
	v_mov_b64_e32 v[34:35], 0
	v_mov_b64_e32 v[36:37], 0
	v_mov_b64_e32 v[38:39], 0
	v_mov_b64_e32 v[40:41], 0
	v_mov_b64_e32 v[50:51], 0
	v_mov_b64_e32 v[52:53], 0
	v_mov_b64_e32 v[54:55], 0
	v_mov_b64_e32 v[56:57], 0
	v_mov_b64_e32 v[10:11], 0
	v_mov_b64_e32 v[12:13], 0
	v_mov_b64_e32 v[14:15], 0
	v_mov_b64_e32 v[16:17], 0
	v_mov_b64_e32 v[26:27], 0
	v_mov_b64_e32 v[28:29], 0
	v_mov_b64_e32 v[30:31], 0
	v_mov_b64_e32 v[32:33], 0
	v_mov_b64_e32 v[42:43], 0
	v_mov_b64_e32 v[44:45], 0
	v_mov_b64_e32 v[46:47], 0
	v_mov_b64_e32 v[48:49], 0
	v_mov_b64_e32 v[58:59], 0
	v_mov_b64_e32 v[60:61], 0
	v_mov_b64_e32 v[62:63], 0
	v_mov_b64_e32 v[64:65], 0
	v_mov_b64_e32 v[66:67], 0
	v_mov_b64_e32 v[68:69], 0
	v_mov_b64_e32 v[70:71], 0
	v_mov_b64_e32 v[72:73], 0
	v_mov_b64_e32 v[82:83], 0
	v_mov_b64_e32 v[84:85], 0
	v_mov_b64_e32 v[86:87], 0
	v_mov_b64_e32 v[88:89], 0
	v_mov_b64_e32 v[98:99], 0
	v_mov_b64_e32 v[100:101], 0
	v_mov_b64_e32 v[102:103], 0
	v_mov_b64_e32 v[104:105], 0
	v_mov_b64_e32 v[114:115], 0
	v_mov_b64_e32 v[116:117], 0
	v_mov_b64_e32 v[118:119], 0
	v_mov_b64_e32 v[120:121], 0
	v_mov_b64_e32 v[74:75], 0
	v_mov_b64_e32 v[76:77], 0
	v_mov_b64_e32 v[78:79], 0
	v_mov_b64_e32 v[80:81], 0
	v_mov_b64_e32 v[90:91], 0
	v_mov_b64_e32 v[92:93], 0
	v_mov_b64_e32 v[94:95], 0
	v_mov_b64_e32 v[96:97], 0
	v_mov_b64_e32 v[106:107], 0
	v_mov_b64_e32 v[108:109], 0
	v_mov_b64_e32 v[110:111], 0
	v_mov_b64_e32 v[112:113], 0
	v_mov_b64_e32 v[122:123], 0
	v_mov_b64_e32 v[124:125], 0
	v_mov_b64_e32 v[126:127], 0
	v_mov_b64_e32 v[128:129], 0
	s_branch .LBB0_370
